# grid barrier: leaders arrive at top counter with non-returning add, all WGs poll it (no TOPGEN/XGEN relay)
# baseline (speedup 1.0000x reference)
; __device__ __forceinline__ unsigned xb_ld(unsigned* p)              { return __hip_atomic_load(p, __ATOMIC_RELAXED, __HIP_MEMORY_SCOPE_AGENT); }
; __device__ __forceinline__ unsigned xb_add(unsigned* p, unsigned v) { return __hip_atomic_fetch_add(p, v, __ATOMIC_RELAXED, __HIP_MEMORY_SCOPE_AGENT); }
; #define XB_SPIN(cond, bar) do { unsigned _sp = 0; while (cond) { __builtin_amdgcn_s_sleep(1); \
;     if ((++_sp & 255u) == 0u) { if (xb_ld(&(bar)[XB_TMO])) break; if (_sp > XB_SPIN_CAP) { atomicAdd(&(bar)[XB_TMO], 1u); break; } } } } while (0)
; __device__ __forceinline__ void xcd_barrier(const XcdBarrier& b) {
;     asm volatile("s_waitcnt vmcnt(0)" ::: "memory");
;     __syncthreads();
;     if (threadIdx.x == 0) {
;         unsigned* bar = b.bar;
;         __builtin_amdgcn_s_waitcnt(0);
;         unsigned nloc = b.st[0], nx = b.st[1];
;         if (nloc == 0u) { xcd_barrier_complete(bar, b.x, nloc, nx); b.st[0] = nloc; b.st[1] = nx; }
;         const unsigned old = xb_add(&bar[XB_XSUB(b.x)], 1u);
;         asm volatile("buffer_inv sc1" ::: "memory");
;         const unsigned gen = old / nloc;
;         if (old + 1u == (gen + 1u) * nloc) {
;             __builtin_amdgcn_fence(__ATOMIC_RELEASE, "agent");
;             asm volatile("s_waitcnt vmcnt(0)" ::: "memory");
;             const unsigned og = xb_add(&bar[XB_TOP], 1u);
;             const unsigned tg = og / nx;
;             if (og + 1u == (tg + 1u) * nx) xb_add(&bar[XB_TOPGEN], 1u);
;             else XB_SPIN(xb_ld(&bar[XB_TOPGEN]) == tg, bar);
;             asm volatile("" ::: "memory");
;             xb_add(&bar[XB_XGEN(b.x)], 1u);
;             asm volatile("s_waitcnt vmcnt(0)" ::: "memory");
;         } else {
;             XB_SPIN(xb_ld(&bar[XB_XGEN(b.x)]) == gen, bar);
;             asm volatile("s_waitcnt vmcnt(0)" ::: "memory");
;         }
;     }
;     __syncthreads();
; }
.LBB0_82:
	s_lshl_b32 s3, s90, 8
	s_add_u32 s8, s58, s3
	s_addc_u32 s9, s59, 0
	v_mov_b32_e32 v2, 0x1000
	v_mov_b32_e32 v4, 1
	global_atomic_add v4, v2, v4, s[8:9] offset:1024 sc0
	v_cvt_f32_u32_e32 v2, v3
	v_sub_u32_e32 v5, 0, v3
	buffer_inv sc1
	v_rcp_iflag_f32_e32 v2, v2
	s_nop 0
	v_mul_f32_e32 v2, 0x4f7ffffe, v2
	v_cvt_u32_f32_e32 v2, v2
	v_mul_lo_u32 v5, v5, v2
	v_mul_hi_u32 v5, v2, v5
	v_add_u32_e32 v2, v2, v5
	s_waitcnt vmcnt(0)
	v_mul_hi_u32 v2, v4, v2
	v_mul_lo_u32 v5, v2, v3
	v_sub_u32_e32 v5, v4, v5
	v_add_u32_e32 v6, 1, v2
	v_cmp_ge_u32_e32 vcc, v5, v3
	v_add_u32_e32 v4, 1, v4
	s_nop 0
	v_cndmask_b32_e32 v2, v2, v6, vcc
	v_sub_u32_e32 v6, v5, v3
	v_cndmask_b32_e32 v5, v5, v6, vcc
	v_add_u32_e32 v6, 1, v2
	v_cmp_ge_u32_e32 vcc, v5, v3
	s_nop 1
	v_cndmask_b32_e32 v2, v2, v6, vcc
	v_mul_lo_u32 v5, v3, v2
	v_add_u32_e32 v3, v5, v3
	v_cmp_ne_u32_e32 vcc, v4, v3
	s_waitcnt lgkmcnt(0)
	v_add_u32_e32 v5, 1, v2
	v_mul_lo_u32 v5, v5, v1
	v_mov_b32_e32 v6, 0x3000
	v_mov_b32_e32 v8, 0
	s_cbranch_vccnz .Lxb1_spin
	buffer_wbl2 sc1
	s_waitcnt vmcnt(0)
	v_mov_b32_e32 v7, 1
	global_atomic_add v6, v7, s[58:59] offset:1024
.Lxb1_spin:
	global_load_dword v7, v6, s[58:59] offset:1024 sc1
	s_waitcnt vmcnt(0)
	v_cmp_ge_u32_e32 vcc, v7, v5
	s_cbranch_vccnz .Lxb1_done
	s_sleep 2
	v_add_u32_e32 v8, 1, v8
	v_cmp_gt_u32_e32 vcc, 0x4000, v8
	s_cbranch_vccnz .Lxb1_spin
	v_mov_b32_e32 v6, 0
	v_mov_b32_e32 v7, 1
	global_atomic_add v6, v7, s[58:59] offset:512
.Lxb1_done:
	s_waitcnt vmcnt(0)
.LBB0_114:
	s_or_b64 exec, exec, s[6:7]
	s_waitcnt lgkmcnt(0)
	s_barrier

; __device__ __forceinline__ unsigned xb_ld(unsigned* p)              { return __hip_atomic_load(p, __ATOMIC_RELAXED, __HIP_MEMORY_SCOPE_AGENT); }
; __device__ __forceinline__ unsigned xb_add(unsigned* p, unsigned v) { return __hip_atomic_fetch_add(p, v, __ATOMIC_RELAXED, __HIP_MEMORY_SCOPE_AGENT); }
; #define XB_SPIN(cond, bar) do { unsigned _sp = 0; while (cond) { __builtin_amdgcn_s_sleep(1); \
;     if ((++_sp & 255u) == 0u) { if (xb_ld(&(bar)[XB_TMO])) break; if (_sp > XB_SPIN_CAP) { atomicAdd(&(bar)[XB_TMO], 1u); break; } } } } while (0)
; __device__ __forceinline__ void xcd_barrier(const XcdBarrier& b) {
;     ...
;             const unsigned tg = og / nx;
;             if (og + 1u == (tg + 1u) * nx) xb_add(&bar[XB_TOPGEN], 1u);
;             else XB_SPIN(xb_ld(&bar[XB_TOPGEN]) == tg, bar);
;             asm volatile("" ::: "memory");
;             xb_add(&bar[XB_XGEN(b.x)], 1u);
;             asm volatile("s_waitcnt vmcnt(0)" ::: "memory");
;         } else {
;             XB_SPIN(xb_ld(&bar[XB_XGEN(b.x)]) == gen, bar);
;             asm volatile("s_waitcnt vmcnt(0)" ::: "memory");
;         }
;     }
;     __syncthreads();
.Lxb2_done:
	s_waitcnt vmcnt(0)
.LBB0_311:
	s_or_b64 exec, exec, s[6:7]
	s_waitcnt lgkmcnt(0)
	s_barrier

; __device__ __forceinline__ unsigned xb_ld(unsigned* p)              { return __hip_atomic_load(p, __ATOMIC_RELAXED, __HIP_MEMORY_SCOPE_AGENT); }
; __device__ __forceinline__ unsigned xb_add(unsigned* p, unsigned v) { return __hip_atomic_fetch_add(p, v, __ATOMIC_RELAXED, __HIP_MEMORY_SCOPE_AGENT); }
; #define XB_SPIN(cond, bar) do { unsigned _sp = 0; while (cond) { __builtin_amdgcn_s_sleep(1); \
;     if ((++_sp & 255u) == 0u) { if (xb_ld(&(bar)[XB_TMO])) break; if (_sp > XB_SPIN_CAP) { atomicAdd(&(bar)[XB_TMO], 1u); break; } } } } while (0)
; __device__ __forceinline__ void xcd_barrier(const XcdBarrier& b) {
;     ...
;             const unsigned tg = og / nx;
;             if (og + 1u == (tg + 1u) * nx) xb_add(&bar[XB_TOPGEN], 1u);
;             else XB_SPIN(xb_ld(&bar[XB_TOPGEN]) == tg, bar);
;             asm volatile("" ::: "memory");
;             xb_add(&bar[XB_XGEN(b.x)], 1u);
;             asm volatile("s_waitcnt vmcnt(0)" ::: "memory");
;         } else {
;             XB_SPIN(xb_ld(&bar[XB_XGEN(b.x)]) == gen, bar);
;             asm volatile("s_waitcnt vmcnt(0)" ::: "memory");
;         }
;     }
;     __syncthreads();
.Lxb3_done:
	s_waitcnt vmcnt(0)
.LBB0_659:
	s_or_b64 exec, exec, s[6:7]
	s_waitcnt lgkmcnt(0)
	s_barrier

; __device__ __forceinline__ unsigned xb_ld(unsigned* p)              { return __hip_atomic_load(p, __ATOMIC_RELAXED, __HIP_MEMORY_SCOPE_AGENT); }
; __device__ __forceinline__ unsigned xb_add(unsigned* p, unsigned v) { return __hip_atomic_fetch_add(p, v, __ATOMIC_RELAXED, __HIP_MEMORY_SCOPE_AGENT); }
; #define XB_SPIN(cond, bar) do { unsigned _sp = 0; while (cond) { __builtin_amdgcn_s_sleep(1); \
;     if ((++_sp & 255u) == 0u) { if (xb_ld(&(bar)[XB_TMO])) break; if (_sp > XB_SPIN_CAP) { atomicAdd(&(bar)[XB_TMO], 1u); break; } } } } while (0)
; __device__ __forceinline__ void xcd_barrier(const XcdBarrier& b) {
;     asm volatile("s_waitcnt vmcnt(0)" ::: "memory");
;     __syncthreads();
;     if (threadIdx.x == 0) {
;         unsigned* bar = b.bar;
;         __builtin_amdgcn_s_waitcnt(0);
;         unsigned nloc = b.st[0], nx = b.st[1];
;         if (nloc == 0u) { xcd_barrier_complete(bar, b.x, nloc, nx); b.st[0] = nloc; b.st[1] = nx; }
;         const unsigned old = xb_add(&bar[XB_XSUB(b.x)], 1u);
;         asm volatile("buffer_inv sc1" ::: "memory");
;         const unsigned gen = old / nloc;
;         if (old + 1u == (gen + 1u) * nloc) {
;             __builtin_amdgcn_fence(__ATOMIC_RELEASE, "agent");
;             asm volatile("s_waitcnt vmcnt(0)" ::: "memory");
;             const unsigned og = xb_add(&bar[XB_TOP], 1u);
;             const unsigned tg = og / nx;
;             if (og + 1u == (tg + 1u) * nx) xb_add(&bar[XB_TOPGEN], 1u);
;             else XB_SPIN(xb_ld(&bar[XB_TOPGEN]) == tg, bar);
;             asm volatile("" ::: "memory");
;             xb_add(&bar[XB_XGEN(b.x)], 1u);
;             asm volatile("s_waitcnt vmcnt(0)" ::: "memory");
;         } else {
;             XB_SPIN(xb_ld(&bar[XB_XGEN(b.x)]) == gen, bar);
;             asm volatile("s_waitcnt vmcnt(0)" ::: "memory");
;         }
;     }
;     __syncthreads();
; }
.LBB0_857:
	s_lshl_b32 s3, s90, 8
	s_add_u32 s6, s58, s3
	s_addc_u32 s7, s59, 0
	v_mov_b32_e32 v2, 0x1000
	v_mov_b32_e32 v4, 1
	global_atomic_add v4, v2, v4, s[6:7] offset:1024 sc0
	v_cvt_f32_u32_e32 v2, v3
	v_sub_u32_e32 v5, 0, v3
	buffer_inv sc1
	v_rcp_iflag_f32_e32 v2, v2
	s_nop 0
	v_mul_f32_e32 v2, 0x4f7ffffe, v2
	v_cvt_u32_f32_e32 v2, v2
	v_mul_lo_u32 v5, v5, v2
	v_mul_hi_u32 v5, v2, v5
	v_add_u32_e32 v2, v2, v5
	s_waitcnt vmcnt(0)
	v_mul_hi_u32 v2, v4, v2
	v_mul_lo_u32 v5, v2, v3
	v_sub_u32_e32 v5, v4, v5
	v_add_u32_e32 v6, 1, v2
	v_cmp_ge_u32_e32 vcc, v5, v3
	v_add_u32_e32 v4, 1, v4
	s_nop 0
	v_cndmask_b32_e32 v2, v2, v6, vcc
	v_sub_u32_e32 v6, v5, v3
	v_cndmask_b32_e32 v5, v5, v6, vcc
	v_add_u32_e32 v6, 1, v2
	v_cmp_ge_u32_e32 vcc, v5, v3
	s_nop 1
	v_cndmask_b32_e32 v2, v2, v6, vcc
	v_mul_lo_u32 v5, v3, v2
	v_add_u32_e32 v3, v5, v3
	v_cmp_ne_u32_e32 vcc, v4, v3
	s_waitcnt lgkmcnt(0)
	v_add_u32_e32 v5, 1, v2
	v_mul_lo_u32 v5, v5, v1
	v_mov_b32_e32 v6, 0x3000
	v_mov_b32_e32 v8, 0
	s_cbranch_vccnz .Lxb4_spin
	buffer_wbl2 sc1
	s_waitcnt vmcnt(0)
	v_mov_b32_e32 v7, 1
	global_atomic_add v6, v7, s[58:59] offset:1024

; __device__ __forceinline__ unsigned xb_ld(unsigned* p)              { return __hip_atomic_load(p, __ATOMIC_RELAXED, __HIP_MEMORY_SCOPE_AGENT); }
; __device__ __forceinline__ unsigned xb_add(unsigned* p, unsigned v) { return __hip_atomic_fetch_add(p, v, __ATOMIC_RELAXED, __HIP_MEMORY_SCOPE_AGENT); }
; #define XB_SPIN(cond, bar) do { unsigned _sp = 0; while (cond) { __builtin_amdgcn_s_sleep(1); \
;     if ((++_sp & 255u) == 0u) { if (xb_ld(&(bar)[XB_TMO])) break; if (_sp > XB_SPIN_CAP) { atomicAdd(&(bar)[XB_TMO], 1u); break; } } } } while (0)
; __device__ __forceinline__ void xcd_barrier(const XcdBarrier& b) {
;     ...
;             const unsigned tg = og / nx;
;             if (og + 1u == (tg + 1u) * nx) xb_add(&bar[XB_TOPGEN], 1u);
;             else XB_SPIN(xb_ld(&bar[XB_TOPGEN]) == tg, bar);
;             asm volatile("" ::: "memory");
;             xb_add(&bar[XB_XGEN(b.x)], 1u);
;             asm volatile("s_waitcnt vmcnt(0)" ::: "memory");
;         } else {
;             XB_SPIN(xb_ld(&bar[XB_XGEN(b.x)]) == gen, bar);
;             asm volatile("s_waitcnt vmcnt(0)" ::: "memory");
;         }
;     }
;     __syncthreads();
.Lxb4_done:
	s_waitcnt vmcnt(0)
.LBB0_889:
	s_or_b64 exec, exec, s[0:1]
	s_waitcnt lgkmcnt(0)
	s_barrier

; __device__ __forceinline__ unsigned xb_ld(unsigned* p)              { return __hip_atomic_load(p, __ATOMIC_RELAXED, __HIP_MEMORY_SCOPE_AGENT); }
; __device__ __forceinline__ unsigned xb_add(unsigned* p, unsigned v) { return __hip_atomic_fetch_add(p, v, __ATOMIC_RELAXED, __HIP_MEMORY_SCOPE_AGENT); }
; #define XB_SPIN(cond, bar) do { unsigned _sp = 0; while (cond) { __builtin_amdgcn_s_sleep(1); \
;     if ((++_sp & 255u) == 0u) { if (xb_ld(&(bar)[XB_TMO])) break; if (_sp > XB_SPIN_CAP) { atomicAdd(&(bar)[XB_TMO], 1u); break; } } } } while (0)
; __device__ __forceinline__ void xcd_barrier(const XcdBarrier& b) {
;     ...
;             const unsigned tg = og / nx;
;             if (og + 1u == (tg + 1u) * nx) xb_add(&bar[XB_TOPGEN], 1u);
;             else XB_SPIN(xb_ld(&bar[XB_TOPGEN]) == tg, bar);
;             asm volatile("" ::: "memory");
;             xb_add(&bar[XB_XGEN(b.x)], 1u);
;             asm volatile("s_waitcnt vmcnt(0)" ::: "memory");
;         } else {
;             XB_SPIN(xb_ld(&bar[XB_XGEN(b.x)]) == gen, bar);
;             asm volatile("s_waitcnt vmcnt(0)" ::: "memory");
;         }
;     }
;     __syncthreads();
.Lxb5_done:
	s_waitcnt vmcnt(0)
.LBB0_945:
	s_or_b64 exec, exec, s[0:1]
	s_waitcnt lgkmcnt(0)
	s_barrier

; __device__ __forceinline__ unsigned xb_ld(unsigned* p)              { return __hip_atomic_load(p, __ATOMIC_RELAXED, __HIP_MEMORY_SCOPE_AGENT); }
; __device__ __forceinline__ unsigned xb_add(unsigned* p, unsigned v) { return __hip_atomic_fetch_add(p, v, __ATOMIC_RELAXED, __HIP_MEMORY_SCOPE_AGENT); }
; #define XB_SPIN(cond, bar) do { unsigned _sp = 0; while (cond) { __builtin_amdgcn_s_sleep(1); \
;     if ((++_sp & 255u) == 0u) { if (xb_ld(&(bar)[XB_TMO])) break; if (_sp > XB_SPIN_CAP) { atomicAdd(&(bar)[XB_TMO], 1u); break; } } } } while (0)
; __device__ __forceinline__ void xcd_barrier(const XcdBarrier& b) {
;     asm volatile("s_waitcnt vmcnt(0)" ::: "memory");
;     __syncthreads();
;     if (threadIdx.x == 0) {
;         unsigned* bar = b.bar;
;         __builtin_amdgcn_s_waitcnt(0);
;         unsigned nloc = b.st[0], nx = b.st[1];
;         if (nloc == 0u) { xcd_barrier_complete(bar, b.x, nloc, nx); b.st[0] = nloc; b.st[1] = nx; }
;         const unsigned old = xb_add(&bar[XB_XSUB(b.x)], 1u);
;         asm volatile("buffer_inv sc1" ::: "memory");
;         const unsigned gen = old / nloc;
;         if (old + 1u == (gen + 1u) * nloc) {
;             __builtin_amdgcn_fence(__ATOMIC_RELEASE, "agent");
;             asm volatile("s_waitcnt vmcnt(0)" ::: "memory");
;             const unsigned og = xb_add(&bar[XB_TOP], 1u);
;             const unsigned tg = og / nx;
;             if (og + 1u == (tg + 1u) * nx) xb_add(&bar[XB_TOPGEN], 1u);
;             else XB_SPIN(xb_ld(&bar[XB_TOPGEN]) == tg, bar);
;             asm volatile("" ::: "memory");
;             xb_add(&bar[XB_XGEN(b.x)], 1u);
;             asm volatile("s_waitcnt vmcnt(0)" ::: "memory");
;         } else {
;             XB_SPIN(xb_ld(&bar[XB_XGEN(b.x)]) == gen, bar);
;             asm volatile("s_waitcnt vmcnt(0)" ::: "memory");
;         }
;     }
;     __syncthreads();
; }
.LBB0_1040:
	s_lshl_b32 s5, s90, 8
	s_add_u32 s6, s58, s5
	s_addc_u32 s7, s59, 0
	v_mov_b32_e32 v2, 0x1000
	v_mov_b32_e32 v4, 1
	global_atomic_add v4, v2, v4, s[6:7] offset:1024 sc0
	v_cvt_f32_u32_e32 v2, v3
	v_sub_u32_e32 v5, 0, v3
	buffer_inv sc1
	v_rcp_iflag_f32_e32 v2, v2
	s_nop 0
	v_mul_f32_e32 v2, 0x4f7ffffe, v2
	v_cvt_u32_f32_e32 v2, v2
	v_mul_lo_u32 v5, v5, v2
	v_mul_hi_u32 v5, v2, v5
	v_add_u32_e32 v2, v2, v5
	s_waitcnt vmcnt(0)
	v_mul_hi_u32 v2, v4, v2
	v_mul_lo_u32 v5, v2, v3
	v_sub_u32_e32 v5, v4, v5
	v_add_u32_e32 v6, 1, v2
	v_cmp_ge_u32_e32 vcc, v5, v3
	v_add_u32_e32 v4, 1, v4
	s_nop 0
	v_cndmask_b32_e32 v2, v2, v6, vcc
	v_sub_u32_e32 v6, v5, v3
	v_cndmask_b32_e32 v5, v5, v6, vcc
	v_add_u32_e32 v6, 1, v2
	v_cmp_ge_u32_e32 vcc, v5, v3
	s_nop 1
	v_cndmask_b32_e32 v2, v2, v6, vcc
	v_mul_lo_u32 v5, v3, v2
	v_add_u32_e32 v3, v5, v3
	v_cmp_ne_u32_e32 vcc, v4, v3
	s_waitcnt lgkmcnt(0)
	v_add_u32_e32 v5, 1, v2
	v_mul_lo_u32 v5, v5, v1
	v_mov_b32_e32 v6, 0x3000
	v_mov_b32_e32 v8, 0
	s_cbranch_vccnz .Lxb6_spin
	buffer_wbl2 sc1
	s_waitcnt vmcnt(0)
	v_mov_b32_e32 v7, 1
	global_atomic_add v6, v7, s[58:59] offset:1024

; __device__ __forceinline__ unsigned xb_ld(unsigned* p)              { return __hip_atomic_load(p, __ATOMIC_RELAXED, __HIP_MEMORY_SCOPE_AGENT); }
; __device__ __forceinline__ unsigned xb_add(unsigned* p, unsigned v) { return __hip_atomic_fetch_add(p, v, __ATOMIC_RELAXED, __HIP_MEMORY_SCOPE_AGENT); }
; #define XB_SPIN(cond, bar) do { unsigned _sp = 0; while (cond) { __builtin_amdgcn_s_sleep(1); \
;     if ((++_sp & 255u) == 0u) { if (xb_ld(&(bar)[XB_TMO])) break; if (_sp > XB_SPIN_CAP) { atomicAdd(&(bar)[XB_TMO], 1u); break; } } } } while (0)
; __device__ __forceinline__ void xcd_barrier(const XcdBarrier& b) {
;     ...
;             const unsigned tg = og / nx;
;             if (og + 1u == (tg + 1u) * nx) xb_add(&bar[XB_TOPGEN], 1u);
;             else XB_SPIN(xb_ld(&bar[XB_TOPGEN]) == tg, bar);
;             asm volatile("" ::: "memory");
;             xb_add(&bar[XB_XGEN(b.x)], 1u);
;             asm volatile("s_waitcnt vmcnt(0)" ::: "memory");
;         } else {
;             XB_SPIN(xb_ld(&bar[XB_XGEN(b.x)]) == gen, bar);
;             asm volatile("s_waitcnt vmcnt(0)" ::: "memory");
;         }
;     }
;     __syncthreads();
.Lxb6_done:
	s_waitcnt vmcnt(0)
.LBB0_1072:
	s_or_b64 exec, exec, s[0:1]
	s_waitcnt lgkmcnt(0)
	s_barrier

; __device__ __forceinline__ unsigned xb_ld(unsigned* p)              { return __hip_atomic_load(p, __ATOMIC_RELAXED, __HIP_MEMORY_SCOPE_AGENT); }
; __device__ __forceinline__ unsigned xb_add(unsigned* p, unsigned v) { return __hip_atomic_fetch_add(p, v, __ATOMIC_RELAXED, __HIP_MEMORY_SCOPE_AGENT); }
; #define XB_SPIN(cond, bar) do { unsigned _sp = 0; while (cond) { __builtin_amdgcn_s_sleep(1); \
;     if ((++_sp & 255u) == 0u) { if (xb_ld(&(bar)[XB_TMO])) break; if (_sp > XB_SPIN_CAP) { atomicAdd(&(bar)[XB_TMO], 1u); break; } } } } while (0)
; __device__ __forceinline__ void xcd_barrier(const XcdBarrier& b) {
;     ...
;             const unsigned tg = og / nx;
;             if (og + 1u == (tg + 1u) * nx) xb_add(&bar[XB_TOPGEN], 1u);
;             else XB_SPIN(xb_ld(&bar[XB_TOPGEN]) == tg, bar);
;             asm volatile("" ::: "memory");
;             xb_add(&bar[XB_XGEN(b.x)], 1u);
;             asm volatile("s_waitcnt vmcnt(0)" ::: "memory");
;         } else {
;             XB_SPIN(xb_ld(&bar[XB_XGEN(b.x)]) == gen, bar);
;             asm volatile("s_waitcnt vmcnt(0)" ::: "memory");
;         }
;     }
;     __syncthreads();
.Lxb7_done:
	s_waitcnt vmcnt(0)
.LBB0_1200:
	s_or_b64 exec, exec, s[0:1]
	s_waitcnt lgkmcnt(0)
	s_barrier

; __device__ __forceinline__ unsigned xb_ld(unsigned* p)              { return __hip_atomic_load(p, __ATOMIC_RELAXED, __HIP_MEMORY_SCOPE_AGENT); }
; __device__ __forceinline__ unsigned xb_add(unsigned* p, unsigned v) { return __hip_atomic_fetch_add(p, v, __ATOMIC_RELAXED, __HIP_MEMORY_SCOPE_AGENT); }
; #define XB_SPIN(cond, bar) do { unsigned _sp = 0; while (cond) { __builtin_amdgcn_s_sleep(1); \
;     if ((++_sp & 255u) == 0u) { if (xb_ld(&(bar)[XB_TMO])) break; if (_sp > XB_SPIN_CAP) { atomicAdd(&(bar)[XB_TMO], 1u); break; } } } } while (0)
; __device__ __forceinline__ void xcd_barrier(const XcdBarrier& b) {
;     asm volatile("s_waitcnt vmcnt(0)" ::: "memory");
;     __syncthreads();
;     if (threadIdx.x == 0) {
;         unsigned* bar = b.bar;
;         __builtin_amdgcn_s_waitcnt(0);
;         unsigned nloc = b.st[0], nx = b.st[1];
;         if (nloc == 0u) { xcd_barrier_complete(bar, b.x, nloc, nx); b.st[0] = nloc; b.st[1] = nx; }
;         const unsigned old = xb_add(&bar[XB_XSUB(b.x)], 1u);
;         asm volatile("buffer_inv sc1" ::: "memory");
;         const unsigned gen = old / nloc;
;         if (old + 1u == (gen + 1u) * nloc) {
;             __builtin_amdgcn_fence(__ATOMIC_RELEASE, "agent");
;             asm volatile("s_waitcnt vmcnt(0)" ::: "memory");
;             const unsigned og = xb_add(&bar[XB_TOP], 1u);
;             const unsigned tg = og / nx;
;             if (og + 1u == (tg + 1u) * nx) xb_add(&bar[XB_TOPGEN], 1u);
;             else XB_SPIN(xb_ld(&bar[XB_TOPGEN]) == tg, bar);
;             asm volatile("" ::: "memory");
;             xb_add(&bar[XB_XGEN(b.x)], 1u);
;             asm volatile("s_waitcnt vmcnt(0)" ::: "memory");
;         } else {
;             XB_SPIN(xb_ld(&bar[XB_XGEN(b.x)]) == gen, bar);
;             asm volatile("s_waitcnt vmcnt(0)" ::: "memory");
;         }
;     }
;     __syncthreads();
; }
.LBB0_1288:
	s_lshl_b32 s3, s90, 8
	s_add_u32 s4, s58, s3
	s_addc_u32 s5, s59, 0
	v_mov_b32_e32 v2, 0x1000
	v_mov_b32_e32 v4, 1
	global_atomic_add v4, v2, v4, s[4:5] offset:1024 sc0
	v_cvt_f32_u32_e32 v2, v3
	v_sub_u32_e32 v5, 0, v3
	buffer_inv sc1
	v_rcp_iflag_f32_e32 v2, v2
	s_nop 0
	v_mul_f32_e32 v2, 0x4f7ffffe, v2
	v_cvt_u32_f32_e32 v2, v2
	v_mul_lo_u32 v5, v5, v2
	v_mul_hi_u32 v5, v2, v5
	v_add_u32_e32 v2, v2, v5
	s_waitcnt vmcnt(0)
	v_mul_hi_u32 v2, v4, v2
	v_mul_lo_u32 v5, v2, v3
	v_sub_u32_e32 v5, v4, v5
	v_add_u32_e32 v6, 1, v2
	v_cmp_ge_u32_e32 vcc, v5, v3
	v_add_u32_e32 v4, 1, v4
	s_nop 0
	v_cndmask_b32_e32 v2, v2, v6, vcc
	v_sub_u32_e32 v6, v5, v3
	v_cndmask_b32_e32 v5, v5, v6, vcc
	v_add_u32_e32 v6, 1, v2
	v_cmp_ge_u32_e32 vcc, v5, v3
	s_nop 1
	v_cndmask_b32_e32 v2, v2, v6, vcc
	v_mul_lo_u32 v5, v3, v2
	v_add_u32_e32 v3, v5, v3
	v_cmp_ne_u32_e32 vcc, v4, v3
	s_waitcnt lgkmcnt(0)
	v_add_u32_e32 v5, 1, v2
	v_mul_lo_u32 v5, v5, v1
	v_mov_b32_e32 v6, 0x3000
	v_mov_b32_e32 v8, 0
	s_cbranch_vccnz .Lxb8_spin
	buffer_wbl2 sc1
	s_waitcnt vmcnt(0)
	v_mov_b32_e32 v7, 1
	global_atomic_add v6, v7, s[58:59] offset:1024

; __device__ __forceinline__ unsigned xb_ld(unsigned* p)              { return __hip_atomic_load(p, __ATOMIC_RELAXED, __HIP_MEMORY_SCOPE_AGENT); }
; __device__ __forceinline__ unsigned xb_add(unsigned* p, unsigned v) { return __hip_atomic_fetch_add(p, v, __ATOMIC_RELAXED, __HIP_MEMORY_SCOPE_AGENT); }
; #define XB_SPIN(cond, bar) do { unsigned _sp = 0; while (cond) { __builtin_amdgcn_s_sleep(1); \
;     if ((++_sp & 255u) == 0u) { if (xb_ld(&(bar)[XB_TMO])) break; if (_sp > XB_SPIN_CAP) { atomicAdd(&(bar)[XB_TMO], 1u); break; } } } } while (0)
; __device__ __forceinline__ void xcd_barrier(const XcdBarrier& b) {
;     ...
;             const unsigned tg = og / nx;
;             if (og + 1u == (tg + 1u) * nx) xb_add(&bar[XB_TOPGEN], 1u);
;             else XB_SPIN(xb_ld(&bar[XB_TOPGEN]) == tg, bar);
;             asm volatile("" ::: "memory");
;             xb_add(&bar[XB_XGEN(b.x)], 1u);
;             asm volatile("s_waitcnt vmcnt(0)" ::: "memory");
;         } else {
;             XB_SPIN(xb_ld(&bar[XB_XGEN(b.x)]) == gen, bar);
;             asm volatile("s_waitcnt vmcnt(0)" ::: "memory");
;         }
;     }
;     __syncthreads();
.Lxb8_done:
	s_waitcnt vmcnt(0)
.LBB0_1320:
	s_or_b64 exec, exec, s[0:1]
	s_waitcnt lgkmcnt(0)
	s_barrier
